# HGRN prep waves touch the cache lines of the chunk two ahead (plain loads, never waited) so the LDS-DMA one chunk ahead hits L2; with V ring, MFMA fold and pipelined act phase
# baseline (speedup 1.0000x reference)
.Lh2_prep:
	v_and_b32_e32 v244, 63, v200
	v_lshrrev_b32_e32 v245, 2, v244
	v_lshrrev_b32_e32 v243, 4, v244
	s_lshl_b32 s1, s8, 12
	s_add_u32 s13, s1, 0xfff
	s_cmp_eq_u32 s12, 0
	s_cselect_b64 s[18:19], -1, 0
	v_mov_b32_e32 v242, 0x1c00
	v_and_b32_e32 v241, 3, v244
	v_and_b32_e32 v240, 3, v243
	v_xor_b32_e32 v241, v241, v240
	v_lshlrev_b32_e32 v241, 4, v241
	v_add_u32_e32 v240, 0, v245
	v_add_u32_e32 v239, s1, v240
	v_sub_u32_e32 v240, s13, v240
	v_cndmask_b32_e64 v239, v240, v239, s[18:19]
	v_mul_lo_u32 v239, v239, v242
	v_add_u32_e32 v228, v239, v241
	v_add_u32_e32 v240, 16, v245
	v_add_u32_e32 v239, s1, v240
	v_sub_u32_e32 v240, s13, v240
	v_cndmask_b32_e64 v239, v240, v239, s[18:19]
	v_mul_lo_u32 v239, v239, v242
	v_add_u32_e32 v230, v239, v241
	v_add_u32_e32 v240, 32, v245
	v_add_u32_e32 v239, s1, v240
	v_sub_u32_e32 v240, s13, v240
	v_cndmask_b32_e64 v239, v240, v239, s[18:19]
	v_mul_lo_u32 v239, v239, v242
	v_add_u32_e32 v231, v239, v241
	v_add_u32_e32 v240, 48, v245
	v_add_u32_e32 v239, s1, v240
	v_sub_u32_e32 v240, s13, v240
	v_cndmask_b32_e64 v239, v240, v239, s[18:19]
	v_mul_lo_u32 v239, v239, v242
	v_add_u32_e32 v232, v239, v241
	s_lshl_b32 s17, s0, 4
	v_add_u32_e32 v240, 0, v243
	v_add_u32_e32 v240, s17, v240
	v_add_u32_e32 v239, s1, v240
	v_sub_u32_e32 v240, s13, v240
	v_cndmask_b32_e64 v239, v240, v239, s[18:19]
	v_mul_lo_u32 v239, v239, v242
	v_lshl_or_b32 v240, v243, 2, 0
	v_and_b32_e32 v238, 15, v244
	v_xor_b32_e32 v240, v240, v238
	v_lshl_add_u32 v252, v240, 4, v239
	v_add_u32_e32 v240, 4, v243
	v_add_u32_e32 v240, s17, v240
	v_add_u32_e32 v239, s1, v240
	v_sub_u32_e32 v240, s13, v240
	v_cndmask_b32_e64 v239, v240, v239, s[18:19]
	v_mul_lo_u32 v239, v239, v242
	v_lshl_or_b32 v240, v243, 2, 1
	v_and_b32_e32 v238, 15, v244
	v_xor_b32_e32 v240, v240, v238
	v_lshl_add_u32 v253, v240, 4, v239
	v_add_u32_e32 v240, 8, v243
	v_add_u32_e32 v240, s17, v240
	v_add_u32_e32 v239, s1, v240
	v_sub_u32_e32 v240, s13, v240
	v_cndmask_b32_e64 v239, v240, v239, s[18:19]
	v_mul_lo_u32 v239, v239, v242
	v_lshl_or_b32 v240, v243, 2, 2
	v_and_b32_e32 v238, 15, v244
	v_xor_b32_e32 v240, v240, v238
	v_lshl_add_u32 v254, v240, 4, v239
	v_add_u32_e32 v240, 12, v243
	v_add_u32_e32 v240, s17, v240
	v_add_u32_e32 v239, s1, v240
	v_sub_u32_e32 v240, s13, v240
	v_cndmask_b32_e64 v239, v240, v239, s[18:19]
	v_mul_lo_u32 v239, v239, v242
	v_lshl_or_b32 v240, v243, 2, 3
	v_and_b32_e32 v238, 15, v244
	v_xor_b32_e32 v240, v240, v238
	v_lshl_add_u32 v255, v240, 4, v239
	s_mov_b32 s33, 0x70000
	s_sub_u32 s13, 0, s33
	s_cmp_eq_u32 s12, 0
	s_cselect_b32 s33, s33, s13
	s_lshl_b32 s13, s9, 8
	s_add_u32 s34, s92, s13
	s_addc_u32 s35, s93, 0
	s_lshl_b32 s1, s0, 6
	s_add_u32 s30, s34, s1
	s_addc_u32 s31, s35, 0
	s_add_u32 s34, s34, 0xc00
	s_addc_u32 s35, s35, 0
	s_movk_i32 s1, 0x800
	s_cmp_eq_u32 s12, 0
	s_cselect_b32 s1, 0x400, s1
	s_add_u32 s14, s30, s1
	s_addc_u32 s15, s31, 0
	v_and_b32_e32 v241, 3, v244
	v_xor_b32_e32 v241, s0, v241
	v_lshlrev_b32_e32 v241, 6, v241
	v_lshl_add_u32 v241, v244, 8, v241
	v_bfe_u32 v240, v244, 2, 2
	v_xor_b32_e32 v239, 0, v240
	v_lshl_add_u32 v222, v239, 4, v241
	v_xor_b32_e32 v239, 1, v240
	v_lshl_add_u32 v223, v239, 4, v241
	v_xor_b32_e32 v239, 2, v240
	v_lshl_add_u32 v224, v239, 4, v241
	v_xor_b32_e32 v239, 3, v240
	v_lshl_add_u32 v225, v239, 4, v241
	v_mov_b32_e32 v239, 0x110
	v_mul_lo_u32 v241, v244, v239
	s_lshl_b32 s1, s0, 6
	v_add_u32_e32 v241, s1, v241
	v_add_u32_e32 v226, 0x10400, v241
	v_add_u32_e32 v227, 0x14800, v241
	s_lshl_b32 s1, s0, 7
	v_mov_b32_e32 v247, s1
	s_lshl_b32 s71, s0, 13
	s_add_u32 s71, s71, 0x1b400
	s_lshl_b32 s72, s0, 12
	v_lshlrev_b32_e32 v241, 6, v244
	v_add_u32_e32 v241, s71, v241
	v_xor_b32_e32 v239, 0, v240
	v_lshl_add_u32 v248, v239, 4, v241
	v_xor_b32_e32 v239, 1, v240
	v_lshl_add_u32 v249, v239, 4, v241
	v_xor_b32_e32 v239, 2, v240
	v_lshl_add_u32 v250, v239, 4, v241
	v_xor_b32_e32 v239, 3, v240
	v_lshl_add_u32 v251, v239, 4, v241
	s_lshl_b32 s1, s8, 12
	s_add_u32 s13, s1, 0xfff
	v_add_u32_e32 v239, s1, v244
	v_sub_u32_e32 v240, s13, v244
	v_cndmask_b32_e64 v239, v240, v239, s[18:19]
	v_mov_b32_e32 v242, 0x1c00
	v_mul_lo_u32 v18, v239, v242
	v_add_u32_e32 v18, s33, v18
	s_mov_b64 s[82:83], s[34:35]
	s_cmp_eq_u32 s0, 1
	s_cbranch_scc0 .Lh2_w1
	s_sub_u32 s82, s30, 64
	s_subb_u32 s83, s31, 0
.Lh2_w1:
	s_cmp_eq_u32 s0, 2
	s_cbranch_scc0 .Lh2_w2
	s_sub_u32 s82, s14, 128
	s_subb_u32 s83, s15, 0
.Lh2_w2:
	s_add_u32 s1, s72, 0x8400
	s_add_u32 m0, s1, 0
	s_nop 0
	global_load_lds_dwordx4 v252, s[34:35]
	s_add_u32 m0, s1, 1024
	s_nop 0
	global_load_lds_dwordx4 v253, s[34:35]
	s_add_u32 m0, s1, 2048
	s_nop 0
	global_load_lds_dwordx4 v254, s[34:35]
	s_add_u32 m0, s1, 3072
	s_nop 0
	global_load_lds_dwordx4 v255, s[34:35]
	v_add_u32_e32 v252, s33, v252
	v_add_u32_e32 v253, s33, v253
	v_add_u32_e32 v254, s33, v254
	v_add_u32_e32 v255, s33, v255
	s_mov_b32 s77, 0xc400
	s_add_u32 m0, s71, 0
	s_nop 0
	global_load_lds_dwordx4 v228, s[14:15]
	s_add_u32 m0, s71, 4096
	s_nop 0
	global_load_lds_dwordx4 v228, s[30:31]
	s_add_u32 m0, s71, 1024
	s_nop 0
	global_load_lds_dwordx4 v230, s[14:15]
	s_add_u32 m0, s71, 5120
	s_nop 0
	global_load_lds_dwordx4 v230, s[30:31]
	s_add_u32 m0, s71, 2048
	s_nop 0
	global_load_lds_dwordx4 v231, s[14:15]
	s_add_u32 m0, s71, 6144
	s_nop 0
	global_load_lds_dwordx4 v231, s[30:31]
	s_add_u32 m0, s71, 3072
	s_nop 0
	global_load_lds_dwordx4 v232, s[14:15]
	s_add_u32 m0, s71, 7168
	s_nop 0
	global_load_lds_dwordx4 v232, s[30:31]
	v_add_u32_e32 v228, s33, v228
	v_add_u32_e32 v230, s33, v230
	v_add_u32_e32 v231, s33, v231
	v_add_u32_e32 v232, s33, v232
	global_load_dword v16, v18, s[82:83]
	global_load_dword v17, v18, s[82:83] offset:128
	v_add_u32_e32 v18, s33, v18
	s_mov_b32 s70, 0
.Lh2_prep_loop:
	s_waitcnt vmcnt(2)
	ds_read_b128 v[234:237], v248
	ds_read_b128 v[238:241], v249
	ds_read_b128 v[242:245], v250
	ds_read_b128 v[168:171], v251
	ds_read_b128 v[0:3], v248 offset:4096
	ds_read_b128 v[4:7], v249 offset:4096
	ds_read_b128 v[8:11], v250 offset:4096
	ds_read_b128 v[12:15], v251 offset:4096
	s_cmp_eq_u32 s70, 31
	s_cselect_b32 s76, 0, s33
	s_add_u32 s1, s72, s77
	s_add_u32 s77, s77, 0x4000
	s_cmp_eq_u32 s77, 0x10400
	s_cselect_b32 s77, 0x24000, s77
	s_cmp_eq_u32 s77, 0x28000
	s_cselect_b32 s77, 0x8400, s77
	s_waitcnt lgkmcnt(4)
	s_add_u32 m0, s1, 0
	s_nop 0
	global_load_lds_dwordx4 v252, s[34:35]
	v_lshlrev_b32_e32 v96, 16, v234
	v_and_b32_e32 v97, 0xffff0000, v234
	v_lshlrev_b32_e32 v98, 16, v235
	v_and_b32_e32 v99, 0xffff0000, v235
	v_lshlrev_b32_e32 v100, 16, v236
	v_and_b32_e32 v101, 0xffff0000, v236
	v_lshlrev_b32_e32 v102, 16, v237
	v_and_b32_e32 v103, 0xffff0000, v237
	v_lshlrev_b32_e32 v104, 16, v238
	v_and_b32_e32 v105, 0xffff0000, v238
	v_lshlrev_b32_e32 v106, 16, v239
	v_and_b32_e32 v107, 0xffff0000, v239
	v_lshlrev_b32_e32 v108, 16, v240
	v_and_b32_e32 v109, 0xffff0000, v240
	v_lshlrev_b32_e32 v110, 16, v241
	v_and_b32_e32 v111, 0xffff0000, v241
	v_lshlrev_b32_e32 v112, 16, v242
	v_and_b32_e32 v113, 0xffff0000, v242
	v_lshlrev_b32_e32 v114, 16, v243
	v_and_b32_e32 v115, 0xffff0000, v243
	v_lshlrev_b32_e32 v116, 16, v244
	s_add_u32 m0, s1, 1024
	s_nop 0
	global_load_lds_dwordx4 v253, s[34:35]
	v_and_b32_e32 v117, 0xffff0000, v244
	v_lshlrev_b32_e32 v118, 16, v245
	v_and_b32_e32 v119, 0xffff0000, v245
	v_lshlrev_b32_e32 v120, 16, v168
	v_and_b32_e32 v121, 0xffff0000, v168
	v_lshlrev_b32_e32 v122, 16, v169
	v_and_b32_e32 v123, 0xffff0000, v169
	v_lshlrev_b32_e32 v124, 16, v170
	v_and_b32_e32 v125, 0xffff0000, v170
	v_lshlrev_b32_e32 v126, 16, v171
	v_and_b32_e32 v127, 0xffff0000, v171
	s_waitcnt lgkmcnt(0)
	v_sub_f32_e32 v128, 1.0, v96
	v_sub_f32_e32 v129, 1.0, v97
	v_sub_f32_e32 v130, 1.0, v98
	v_sub_f32_e32 v131, 1.0, v99
	v_sub_f32_e32 v132, 1.0, v100
	v_sub_f32_e32 v133, 1.0, v101
	v_sub_f32_e32 v134, 1.0, v102
	v_sub_f32_e32 v135, 1.0, v103
	v_sub_f32_e32 v136, 1.0, v104
	v_sub_f32_e32 v137, 1.0, v105
	s_add_u32 m0, s1, 2048
	s_nop 0
	global_load_lds_dwordx4 v254, s[34:35]
	v_sub_f32_e32 v138, 1.0, v106
	v_sub_f32_e32 v139, 1.0, v107
	v_sub_f32_e32 v140, 1.0, v108
	v_sub_f32_e32 v141, 1.0, v109
	v_sub_f32_e32 v142, 1.0, v110
	v_sub_f32_e32 v143, 1.0, v111
	v_sub_f32_e32 v144, 1.0, v112
	v_sub_f32_e32 v145, 1.0, v113
	v_sub_f32_e32 v146, 1.0, v114
	v_sub_f32_e32 v147, 1.0, v115
	v_sub_f32_e32 v148, 1.0, v116
	v_sub_f32_e32 v149, 1.0, v117
	v_sub_f32_e32 v150, 1.0, v118
	v_sub_f32_e32 v151, 1.0, v119
	v_sub_f32_e32 v152, 1.0, v120
	v_sub_f32_e32 v153, 1.0, v121
	v_sub_f32_e32 v154, 1.0, v122
	v_sub_f32_e32 v155, 1.0, v123
	v_sub_f32_e32 v156, 1.0, v124
	v_sub_f32_e32 v157, 1.0, v125
	v_sub_f32_e32 v158, 1.0, v126
	s_add_u32 m0, s1, 3072
	s_nop 0
	global_load_lds_dwordx4 v255, s[34:35]
	v_add_u32_e32 v252, s76, v252
	v_add_u32_e32 v253, s76, v253
	v_add_u32_e32 v254, s76, v254
	v_add_u32_e32 v255, s76, v255
	v_sub_f32_e32 v159, 1.0, v127
	v_mul_f32_dpp v128, v128, v128 row_shr:1 row_mask:0xf bank_mask:0xf
	v_mul_f32_dpp v129, v129, v129 row_shr:1 row_mask:0xf bank_mask:0xf
	v_mul_f32_dpp v130, v130, v130 row_shr:1 row_mask:0xf bank_mask:0xf
	v_mul_f32_dpp v131, v131, v131 row_shr:1 row_mask:0xf bank_mask:0xf
	v_mul_f32_dpp v132, v132, v132 row_shr:1 row_mask:0xf bank_mask:0xf
	v_mul_f32_dpp v133, v133, v133 row_shr:1 row_mask:0xf bank_mask:0xf
	v_mul_f32_dpp v134, v134, v134 row_shr:1 row_mask:0xf bank_mask:0xf
	v_mul_f32_dpp v135, v135, v135 row_shr:1 row_mask:0xf bank_mask:0xf
	v_mul_f32_dpp v136, v136, v136 row_shr:1 row_mask:0xf bank_mask:0xf
	v_mul_f32_dpp v137, v137, v137 row_shr:1 row_mask:0xf bank_mask:0xf
	v_mul_f32_dpp v138, v138, v138 row_shr:1 row_mask:0xf bank_mask:0xf
	v_mul_f32_dpp v139, v139, v139 row_shr:1 row_mask:0xf bank_mask:0xf
	v_mul_f32_dpp v140, v140, v140 row_shr:1 row_mask:0xf bank_mask:0xf
	v_mul_f32_dpp v141, v141, v141 row_shr:1 row_mask:0xf bank_mask:0xf
	v_mul_f32_dpp v142, v142, v142 row_shr:1 row_mask:0xf bank_mask:0xf
	v_mul_f32_dpp v143, v143, v143 row_shr:1 row_mask:0xf bank_mask:0xf
	v_mul_f32_dpp v144, v144, v144 row_shr:1 row_mask:0xf bank_mask:0xf
	v_mul_f32_dpp v145, v145, v145 row_shr:1 row_mask:0xf bank_mask:0xf
	v_mul_f32_dpp v146, v146, v146 row_shr:1 row_mask:0xf bank_mask:0xf
	v_mul_f32_dpp v147, v147, v147 row_shr:1 row_mask:0xf bank_mask:0xf
	s_add_u32 m0, s71, 0
	s_nop 0
	global_load_lds_dwordx4 v228, s[14:15]
	v_mul_f32_dpp v148, v148, v148 row_shr:1 row_mask:0xf bank_mask:0xf
	v_mul_f32_dpp v149, v149, v149 row_shr:1 row_mask:0xf bank_mask:0xf
	v_mul_f32_dpp v150, v150, v150 row_shr:1 row_mask:0xf bank_mask:0xf
	v_mul_f32_dpp v151, v151, v151 row_shr:1 row_mask:0xf bank_mask:0xf
	v_mul_f32_dpp v152, v152, v152 row_shr:1 row_mask:0xf bank_mask:0xf
	v_mul_f32_dpp v153, v153, v153 row_shr:1 row_mask:0xf bank_mask:0xf
	v_mul_f32_dpp v154, v154, v154 row_shr:1 row_mask:0xf bank_mask:0xf
	v_mul_f32_dpp v155, v155, v155 row_shr:1 row_mask:0xf bank_mask:0xf
	v_mul_f32_dpp v156, v156, v156 row_shr:1 row_mask:0xf bank_mask:0xf
	v_mul_f32_dpp v157, v157, v157 row_shr:1 row_mask:0xf bank_mask:0xf
	v_mul_f32_dpp v158, v158, v158 row_shr:1 row_mask:0xf bank_mask:0xf
	v_mul_f32_dpp v159, v159, v159 row_shr:1 row_mask:0xf bank_mask:0xf
	v_mul_f32_dpp v128, v128, v128 row_shr:2 row_mask:0xf bank_mask:0xf
	v_mul_f32_dpp v129, v129, v129 row_shr:2 row_mask:0xf bank_mask:0xf
	v_mul_f32_dpp v130, v130, v130 row_shr:2 row_mask:0xf bank_mask:0xf
	v_mul_f32_dpp v131, v131, v131 row_shr:2 row_mask:0xf bank_mask:0xf
	v_mul_f32_dpp v132, v132, v132 row_shr:2 row_mask:0xf bank_mask:0xf
	v_mul_f32_dpp v133, v133, v133 row_shr:2 row_mask:0xf bank_mask:0xf
	v_mul_f32_dpp v134, v134, v134 row_shr:2 row_mask:0xf bank_mask:0xf
	v_mul_f32_dpp v135, v135, v135 row_shr:2 row_mask:0xf bank_mask:0xf
	v_mul_f32_dpp v136, v136, v136 row_shr:2 row_mask:0xf bank_mask:0xf
	s_add_u32 m0, s71, 4096
	s_nop 0
	global_load_lds_dwordx4 v228, s[30:31]
	v_mul_f32_dpp v137, v137, v137 row_shr:2 row_mask:0xf bank_mask:0xf
	v_mul_f32_dpp v138, v138, v138 row_shr:2 row_mask:0xf bank_mask:0xf
	v_mul_f32_dpp v139, v139, v139 row_shr:2 row_mask:0xf bank_mask:0xf
	v_mul_f32_dpp v140, v140, v140 row_shr:2 row_mask:0xf bank_mask:0xf
	v_mul_f32_dpp v141, v141, v141 row_shr:2 row_mask:0xf bank_mask:0xf
	v_mul_f32_dpp v142, v142, v142 row_shr:2 row_mask:0xf bank_mask:0xf
	v_mul_f32_dpp v143, v143, v143 row_shr:2 row_mask:0xf bank_mask:0xf
	v_mul_f32_dpp v144, v144, v144 row_shr:2 row_mask:0xf bank_mask:0xf
	v_mul_f32_dpp v145, v145, v145 row_shr:2 row_mask:0xf bank_mask:0xf
	v_mul_f32_dpp v146, v146, v146 row_shr:2 row_mask:0xf bank_mask:0xf
	v_mul_f32_dpp v147, v147, v147 row_shr:2 row_mask:0xf bank_mask:0xf
	v_mul_f32_dpp v148, v148, v148 row_shr:2 row_mask:0xf bank_mask:0xf
	v_mul_f32_dpp v149, v149, v149 row_shr:2 row_mask:0xf bank_mask:0xf
	v_mul_f32_dpp v150, v150, v150 row_shr:2 row_mask:0xf bank_mask:0xf
	v_mul_f32_dpp v151, v151, v151 row_shr:2 row_mask:0xf bank_mask:0xf
	v_mul_f32_dpp v152, v152, v152 row_shr:2 row_mask:0xf bank_mask:0xf
	v_mul_f32_dpp v153, v153, v153 row_shr:2 row_mask:0xf bank_mask:0xf
	v_mul_f32_dpp v154, v154, v154 row_shr:2 row_mask:0xf bank_mask:0xf
	v_mul_f32_dpp v155, v155, v155 row_shr:2 row_mask:0xf bank_mask:0xf
	v_mul_f32_dpp v156, v156, v156 row_shr:2 row_mask:0xf bank_mask:0xf
	v_mul_f32_dpp v157, v157, v157 row_shr:2 row_mask:0xf bank_mask:0xf
	s_add_u32 m0, s71, 1024
	s_nop 0
	global_load_lds_dwordx4 v230, s[14:15]
	v_mul_f32_dpp v158, v158, v158 row_shr:2 row_mask:0xf bank_mask:0xf
	v_mul_f32_dpp v159, v159, v159 row_shr:2 row_mask:0xf bank_mask:0xf
	v_mul_f32_dpp v128, v128, v128 row_shr:4 row_mask:0xf bank_mask:0xf
	v_mul_f32_dpp v129, v129, v129 row_shr:4 row_mask:0xf bank_mask:0xf
	v_mul_f32_dpp v130, v130, v130 row_shr:4 row_mask:0xf bank_mask:0xf
	v_mul_f32_dpp v131, v131, v131 row_shr:4 row_mask:0xf bank_mask:0xf
	v_mul_f32_dpp v132, v132, v132 row_shr:4 row_mask:0xf bank_mask:0xf
	v_mul_f32_dpp v133, v133, v133 row_shr:4 row_mask:0xf bank_mask:0xf
	v_mul_f32_dpp v134, v134, v134 row_shr:4 row_mask:0xf bank_mask:0xf
	v_mul_f32_dpp v135, v135, v135 row_shr:4 row_mask:0xf bank_mask:0xf
	v_mul_f32_dpp v136, v136, v136 row_shr:4 row_mask:0xf bank_mask:0xf
	v_mul_f32_dpp v137, v137, v137 row_shr:4 row_mask:0xf bank_mask:0xf
	v_mul_f32_dpp v138, v138, v138 row_shr:4 row_mask:0xf bank_mask:0xf
	v_mul_f32_dpp v139, v139, v139 row_shr:4 row_mask:0xf bank_mask:0xf
	v_mul_f32_dpp v140, v140, v140 row_shr:4 row_mask:0xf bank_mask:0xf
	v_mul_f32_dpp v141, v141, v141 row_shr:4 row_mask:0xf bank_mask:0xf
	v_mul_f32_dpp v142, v142, v142 row_shr:4 row_mask:0xf bank_mask:0xf
	v_mul_f32_dpp v143, v143, v143 row_shr:4 row_mask:0xf bank_mask:0xf
	v_mul_f32_dpp v144, v144, v144 row_shr:4 row_mask:0xf bank_mask:0xf
	v_mul_f32_dpp v145, v145, v145 row_shr:4 row_mask:0xf bank_mask:0xf
	v_mul_f32_dpp v146, v146, v146 row_shr:4 row_mask:0xf bank_mask:0xf
	s_add_u32 m0, s71, 5120
	s_nop 0
	global_load_lds_dwordx4 v230, s[30:31]
	v_mul_f32_dpp v147, v147, v147 row_shr:4 row_mask:0xf bank_mask:0xf
	v_mul_f32_dpp v148, v148, v148 row_shr:4 row_mask:0xf bank_mask:0xf
	v_mul_f32_dpp v149, v149, v149 row_shr:4 row_mask:0xf bank_mask:0xf
	v_mul_f32_dpp v150, v150, v150 row_shr:4 row_mask:0xf bank_mask:0xf
	v_mul_f32_dpp v151, v151, v151 row_shr:4 row_mask:0xf bank_mask:0xf
	v_mul_f32_dpp v152, v152, v152 row_shr:4 row_mask:0xf bank_mask:0xf
	v_mul_f32_dpp v153, v153, v153 row_shr:4 row_mask:0xf bank_mask:0xf
	v_mul_f32_dpp v154, v154, v154 row_shr:4 row_mask:0xf bank_mask:0xf
	v_mul_f32_dpp v155, v155, v155 row_shr:4 row_mask:0xf bank_mask:0xf
	v_mul_f32_dpp v156, v156, v156 row_shr:4 row_mask:0xf bank_mask:0xf
	v_mul_f32_dpp v157, v157, v157 row_shr:4 row_mask:0xf bank_mask:0xf
	v_mul_f32_dpp v158, v158, v158 row_shr:4 row_mask:0xf bank_mask:0xf
	v_mul_f32_dpp v159, v159, v159 row_shr:4 row_mask:0xf bank_mask:0xf
	v_mul_f32_dpp v128, v128, v128 row_shr:8 row_mask:0xf bank_mask:0xf
	v_mul_f32_dpp v129, v129, v129 row_shr:8 row_mask:0xf bank_mask:0xf
	v_mul_f32_dpp v130, v130, v130 row_shr:8 row_mask:0xf bank_mask:0xf
	v_mul_f32_dpp v131, v131, v131 row_shr:8 row_mask:0xf bank_mask:0xf
	v_mul_f32_dpp v132, v132, v132 row_shr:8 row_mask:0xf bank_mask:0xf
	v_mul_f32_dpp v133, v133, v133 row_shr:8 row_mask:0xf bank_mask:0xf
	v_mul_f32_dpp v134, v134, v134 row_shr:8 row_mask:0xf bank_mask:0xf
	v_mul_f32_dpp v135, v135, v135 row_shr:8 row_mask:0xf bank_mask:0xf
	s_add_u32 m0, s71, 2048
	s_nop 0
	global_load_lds_dwordx4 v231, s[14:15]
	v_mul_f32_dpp v136, v136, v136 row_shr:8 row_mask:0xf bank_mask:0xf
	v_mul_f32_dpp v137, v137, v137 row_shr:8 row_mask:0xf bank_mask:0xf
	v_mul_f32_dpp v138, v138, v138 row_shr:8 row_mask:0xf bank_mask:0xf
	v_mul_f32_dpp v139, v139, v139 row_shr:8 row_mask:0xf bank_mask:0xf
	v_mul_f32_dpp v140, v140, v140 row_shr:8 row_mask:0xf bank_mask:0xf
	v_mul_f32_dpp v141, v141, v141 row_shr:8 row_mask:0xf bank_mask:0xf
	v_mul_f32_dpp v142, v142, v142 row_shr:8 row_mask:0xf bank_mask:0xf
	v_mul_f32_dpp v143, v143, v143 row_shr:8 row_mask:0xf bank_mask:0xf
	v_mul_f32_dpp v144, v144, v144 row_shr:8 row_mask:0xf bank_mask:0xf
	v_mul_f32_dpp v145, v145, v145 row_shr:8 row_mask:0xf bank_mask:0xf
	v_mul_f32_dpp v146, v146, v146 row_shr:8 row_mask:0xf bank_mask:0xf
	v_mul_f32_dpp v147, v147, v147 row_shr:8 row_mask:0xf bank_mask:0xf
	v_mul_f32_dpp v148, v148, v148 row_shr:8 row_mask:0xf bank_mask:0xf
	v_mul_f32_dpp v149, v149, v149 row_shr:8 row_mask:0xf bank_mask:0xf
	v_mul_f32_dpp v150, v150, v150 row_shr:8 row_mask:0xf bank_mask:0xf
	v_mul_f32_dpp v151, v151, v151 row_shr:8 row_mask:0xf bank_mask:0xf
	v_mul_f32_dpp v152, v152, v152 row_shr:8 row_mask:0xf bank_mask:0xf
	v_mul_f32_dpp v153, v153, v153 row_shr:8 row_mask:0xf bank_mask:0xf
	v_mul_f32_dpp v154, v154, v154 row_shr:8 row_mask:0xf bank_mask:0xf
	v_mul_f32_dpp v155, v155, v155 row_shr:8 row_mask:0xf bank_mask:0xf
	v_mul_f32_dpp v156, v156, v156 row_shr:8 row_mask:0xf bank_mask:0xf
	s_add_u32 m0, s71, 6144
	s_nop 0
	global_load_lds_dwordx4 v231, s[30:31]
	v_mul_f32_dpp v157, v157, v157 row_shr:8 row_mask:0xf bank_mask:0xf
	v_mul_f32_dpp v158, v158, v158 row_shr:8 row_mask:0xf bank_mask:0xf
	v_mul_f32_dpp v159, v159, v159 row_shr:8 row_mask:0xf bank_mask:0xf
	v_mul_f32_dpp v128, v128, v128 row_bcast:15 row_mask:0xa bank_mask:0xf
	v_mul_f32_dpp v129, v129, v129 row_bcast:15 row_mask:0xa bank_mask:0xf
	v_mul_f32_dpp v130, v130, v130 row_bcast:15 row_mask:0xa bank_mask:0xf
	v_mul_f32_dpp v131, v131, v131 row_bcast:15 row_mask:0xa bank_mask:0xf
	v_mul_f32_dpp v132, v132, v132 row_bcast:15 row_mask:0xa bank_mask:0xf
	v_mul_f32_dpp v133, v133, v133 row_bcast:15 row_mask:0xa bank_mask:0xf
	v_mul_f32_dpp v134, v134, v134 row_bcast:15 row_mask:0xa bank_mask:0xf
	v_mul_f32_dpp v135, v135, v135 row_bcast:15 row_mask:0xa bank_mask:0xf
	v_mul_f32_dpp v136, v136, v136 row_bcast:15 row_mask:0xa bank_mask:0xf
	v_mul_f32_dpp v137, v137, v137 row_bcast:15 row_mask:0xa bank_mask:0xf
	v_mul_f32_dpp v138, v138, v138 row_bcast:15 row_mask:0xa bank_mask:0xf
	v_mul_f32_dpp v139, v139, v139 row_bcast:15 row_mask:0xa bank_mask:0xf
	v_mul_f32_dpp v140, v140, v140 row_bcast:15 row_mask:0xa bank_mask:0xf
	v_mul_f32_dpp v141, v141, v141 row_bcast:15 row_mask:0xa bank_mask:0xf
	v_mul_f32_dpp v142, v142, v142 row_bcast:15 row_mask:0xa bank_mask:0xf
	v_mul_f32_dpp v143, v143, v143 row_bcast:15 row_mask:0xa bank_mask:0xf
	v_mul_f32_dpp v144, v144, v144 row_bcast:15 row_mask:0xa bank_mask:0xf
	v_mul_f32_dpp v145, v145, v145 row_bcast:15 row_mask:0xa bank_mask:0xf
	s_add_u32 m0, s71, 3072
	s_nop 0
	global_load_lds_dwordx4 v232, s[14:15]
	v_mul_f32_dpp v146, v146, v146 row_bcast:15 row_mask:0xa bank_mask:0xf
	v_mul_f32_dpp v147, v147, v147 row_bcast:15 row_mask:0xa bank_mask:0xf
	v_mul_f32_dpp v148, v148, v148 row_bcast:15 row_mask:0xa bank_mask:0xf
	v_mul_f32_dpp v149, v149, v149 row_bcast:15 row_mask:0xa bank_mask:0xf
	v_mul_f32_dpp v150, v150, v150 row_bcast:15 row_mask:0xa bank_mask:0xf
	v_mul_f32_dpp v151, v151, v151 row_bcast:15 row_mask:0xa bank_mask:0xf
	v_mul_f32_dpp v152, v152, v152 row_bcast:15 row_mask:0xa bank_mask:0xf
	v_mul_f32_dpp v153, v153, v153 row_bcast:15 row_mask:0xa bank_mask:0xf
	v_mul_f32_dpp v154, v154, v154 row_bcast:15 row_mask:0xa bank_mask:0xf
	v_mul_f32_dpp v155, v155, v155 row_bcast:15 row_mask:0xa bank_mask:0xf
	v_mul_f32_dpp v156, v156, v156 row_bcast:15 row_mask:0xa bank_mask:0xf
	v_mul_f32_dpp v157, v157, v157 row_bcast:15 row_mask:0xa bank_mask:0xf
	v_mul_f32_dpp v158, v158, v158 row_bcast:15 row_mask:0xa bank_mask:0xf
	v_mul_f32_dpp v159, v159, v159 row_bcast:15 row_mask:0xa bank_mask:0xf
	v_mul_f32_dpp v128, v128, v128 row_bcast:31 row_mask:0xc bank_mask:0xf
	v_mul_f32_dpp v129, v129, v129 row_bcast:31 row_mask:0xc bank_mask:0xf
	v_mul_f32_dpp v130, v130, v130 row_bcast:31 row_mask:0xc bank_mask:0xf
	v_mul_f32_dpp v131, v131, v131 row_bcast:31 row_mask:0xc bank_mask:0xf
	v_mul_f32_dpp v132, v132, v132 row_bcast:31 row_mask:0xc bank_mask:0xf
	v_mul_f32_dpp v133, v133, v133 row_bcast:31 row_mask:0xc bank_mask:0xf
	v_mul_f32_dpp v134, v134, v134 row_bcast:31 row_mask:0xc bank_mask:0xf
	s_add_u32 m0, s71, 7168
	s_nop 0
	global_load_lds_dwordx4 v232, s[30:31]
	v_add_u32_e32 v228, s76, v228
	v_add_u32_e32 v230, s76, v230
	v_add_u32_e32 v231, s76, v231
	v_add_u32_e32 v232, s76, v232
	v_mul_f32_dpp v135, v135, v135 row_bcast:31 row_mask:0xc bank_mask:0xf
	v_mul_f32_dpp v136, v136, v136 row_bcast:31 row_mask:0xc bank_mask:0xf
	v_mul_f32_dpp v137, v137, v137 row_bcast:31 row_mask:0xc bank_mask:0xf
	v_mul_f32_dpp v138, v138, v138 row_bcast:31 row_mask:0xc bank_mask:0xf
	v_mul_f32_dpp v139, v139, v139 row_bcast:31 row_mask:0xc bank_mask:0xf
	v_mul_f32_dpp v140, v140, v140 row_bcast:31 row_mask:0xc bank_mask:0xf
	v_mul_f32_dpp v141, v141, v141 row_bcast:31 row_mask:0xc bank_mask:0xf
	v_mul_f32_dpp v142, v142, v142 row_bcast:31 row_mask:0xc bank_mask:0xf
	v_mul_f32_dpp v143, v143, v143 row_bcast:31 row_mask:0xc bank_mask:0xf
	v_mul_f32_dpp v144, v144, v144 row_bcast:31 row_mask:0xc bank_mask:0xf
	v_mul_f32_dpp v145, v145, v145 row_bcast:31 row_mask:0xc bank_mask:0xf
	v_mul_f32_dpp v146, v146, v146 row_bcast:31 row_mask:0xc bank_mask:0xf
	v_mul_f32_dpp v147, v147, v147 row_bcast:31 row_mask:0xc bank_mask:0xf
	v_mul_f32_dpp v148, v148, v148 row_bcast:31 row_mask:0xc bank_mask:0xf
	v_mul_f32_dpp v149, v149, v149 row_bcast:31 row_mask:0xc bank_mask:0xf
	v_mul_f32_dpp v150, v150, v150 row_bcast:31 row_mask:0xc bank_mask:0xf
	v_mul_f32_dpp v151, v151, v151 row_bcast:31 row_mask:0xc bank_mask:0xf
	v_mul_f32_dpp v152, v152, v152 row_bcast:31 row_mask:0xc bank_mask:0xf
	v_mul_f32_dpp v153, v153, v153 row_bcast:31 row_mask:0xc bank_mask:0xf
	v_mul_f32_dpp v154, v154, v154 row_bcast:31 row_mask:0xc bank_mask:0xf
	v_mul_f32_dpp v155, v155, v155 row_bcast:31 row_mask:0xc bank_mask:0xf
	v_mul_f32_dpp v156, v156, v156 row_bcast:31 row_mask:0xc bank_mask:0xf
	v_mul_f32_dpp v157, v157, v157 row_bcast:31 row_mask:0xc bank_mask:0xf
	v_mul_f32_dpp v158, v158, v158 row_bcast:31 row_mask:0xc bank_mask:0xf
	v_mul_f32_dpp v159, v159, v159 row_bcast:31 row_mask:0xc bank_mask:0xf
	s_cmp_ge_u32 s70, 31
	s_cselect_b32 s75, 0, s33
	global_load_dword v16, v18, s[82:83]
	global_load_dword v17, v18, s[82:83] offset:128
	v_add_u32_e32 v18, s75, v18
	s_mov_b32 exec_lo, 0
	s_brev_b32 exec_hi, 1
	ds_write_b128 v247, v[128:131] offset:0
	ds_write_b128 v247, v[132:135] offset:16
	ds_write_b128 v247, v[136:139] offset:32
	ds_write_b128 v247, v[140:143] offset:48
	ds_write_b128 v247, v[144:147] offset:64
	ds_write_b128 v247, v[148:151] offset:80
	ds_write_b128 v247, v[152:155] offset:96
	ds_write_b128 v247, v[156:159] offset:112
	s_mov_b64 exec, -1
	v_rcp_f32_e32 v220, v128
	v_rcp_f32_e32 v221, v129
	v_lshlrev_b32_e32 v218, 16, v0
	v_and_b32_e32 v219, 0xffff0000, v0
	v_pk_mul_f32 v[218:219], v[128:129], v[218:219]
	v_pk_mul_f32 v[220:221], v[220:221], v[96:97]
	v_cvt_pk_bf16_f32 v202, v218, v219
	v_cvt_pk_bf16_f32 v184, v220, v221
	v_rcp_f32_e32 v220, v130
	v_rcp_f32_e32 v221, v131
	v_lshlrev_b32_e32 v218, 16, v1
	v_and_b32_e32 v219, 0xffff0000, v1
	v_pk_mul_f32 v[218:219], v[130:131], v[218:219]
	v_pk_mul_f32 v[220:221], v[220:221], v[98:99]
	v_cvt_pk_bf16_f32 v203, v218, v219
	v_cvt_pk_bf16_f32 v185, v220, v221
	v_rcp_f32_e32 v220, v132
	v_rcp_f32_e32 v221, v133
	v_lshlrev_b32_e32 v218, 16, v2
	v_and_b32_e32 v219, 0xffff0000, v2
	v_pk_mul_f32 v[218:219], v[132:133], v[218:219]
	v_pk_mul_f32 v[220:221], v[220:221], v[100:101]
	v_cvt_pk_bf16_f32 v204, v218, v219
	v_cvt_pk_bf16_f32 v186, v220, v221
	v_rcp_f32_e32 v220, v134
	v_rcp_f32_e32 v221, v135
	v_lshlrev_b32_e32 v218, 16, v3
	v_and_b32_e32 v219, 0xffff0000, v3
	v_pk_mul_f32 v[218:219], v[134:135], v[218:219]
	v_pk_mul_f32 v[220:221], v[220:221], v[102:103]
	v_cvt_pk_bf16_f32 v205, v218, v219
	v_cvt_pk_bf16_f32 v187, v220, v221
	v_rcp_f32_e32 v220, v136
	v_rcp_f32_e32 v221, v137
	v_lshlrev_b32_e32 v218, 16, v4
	v_and_b32_e32 v219, 0xffff0000, v4
	v_pk_mul_f32 v[218:219], v[136:137], v[218:219]
	v_pk_mul_f32 v[220:221], v[220:221], v[104:105]
	v_cvt_pk_bf16_f32 v206, v218, v219
	v_cvt_pk_bf16_f32 v188, v220, v221
	v_rcp_f32_e32 v220, v138
	v_rcp_f32_e32 v221, v139
	v_lshlrev_b32_e32 v218, 16, v5
	v_and_b32_e32 v219, 0xffff0000, v5
	v_pk_mul_f32 v[218:219], v[138:139], v[218:219]
	v_pk_mul_f32 v[220:221], v[220:221], v[106:107]
	v_cvt_pk_bf16_f32 v207, v218, v219
	v_cvt_pk_bf16_f32 v189, v220, v221
	v_rcp_f32_e32 v220, v140
	v_rcp_f32_e32 v221, v141
	v_lshlrev_b32_e32 v218, 16, v6
	v_and_b32_e32 v219, 0xffff0000, v6
	v_pk_mul_f32 v[218:219], v[140:141], v[218:219]
	v_pk_mul_f32 v[220:221], v[220:221], v[108:109]
	v_cvt_pk_bf16_f32 v208, v218, v219
	v_cvt_pk_bf16_f32 v190, v220, v221
	v_rcp_f32_e32 v220, v142
	v_rcp_f32_e32 v221, v143
	v_lshlrev_b32_e32 v218, 16, v7
	v_and_b32_e32 v219, 0xffff0000, v7
	v_pk_mul_f32 v[218:219], v[142:143], v[218:219]
	v_pk_mul_f32 v[220:221], v[220:221], v[110:111]
	v_cvt_pk_bf16_f32 v209, v218, v219
	v_cvt_pk_bf16_f32 v191, v220, v221
	v_rcp_f32_e32 v220, v144
	v_rcp_f32_e32 v221, v145
	v_lshlrev_b32_e32 v218, 16, v8
	v_and_b32_e32 v219, 0xffff0000, v8
	v_pk_mul_f32 v[218:219], v[144:145], v[218:219]
	v_pk_mul_f32 v[220:221], v[220:221], v[112:113]
	v_cvt_pk_bf16_f32 v210, v218, v219
	v_cvt_pk_bf16_f32 v192, v220, v221
	v_rcp_f32_e32 v220, v146
	v_rcp_f32_e32 v221, v147
	v_lshlrev_b32_e32 v218, 16, v9
	v_and_b32_e32 v219, 0xffff0000, v9
	v_pk_mul_f32 v[218:219], v[146:147], v[218:219]
	v_pk_mul_f32 v[220:221], v[220:221], v[114:115]
	v_cvt_pk_bf16_f32 v211, v218, v219
	v_cvt_pk_bf16_f32 v193, v220, v221
	v_rcp_f32_e32 v220, v148
	v_rcp_f32_e32 v221, v149
	v_lshlrev_b32_e32 v218, 16, v10
	v_and_b32_e32 v219, 0xffff0000, v10
	v_pk_mul_f32 v[218:219], v[148:149], v[218:219]
	v_pk_mul_f32 v[220:221], v[220:221], v[116:117]
	v_cvt_pk_bf16_f32 v212, v218, v219
	v_cvt_pk_bf16_f32 v194, v220, v221
	v_rcp_f32_e32 v220, v150
	v_rcp_f32_e32 v221, v151
	v_lshlrev_b32_e32 v218, 16, v11
	v_and_b32_e32 v219, 0xffff0000, v11
	v_pk_mul_f32 v[218:219], v[150:151], v[218:219]
	v_pk_mul_f32 v[220:221], v[220:221], v[118:119]
	v_cvt_pk_bf16_f32 v213, v218, v219
	v_cvt_pk_bf16_f32 v195, v220, v221
	v_rcp_f32_e32 v220, v152
	v_rcp_f32_e32 v221, v153
	v_lshlrev_b32_e32 v218, 16, v12
	v_and_b32_e32 v219, 0xffff0000, v12
	v_pk_mul_f32 v[218:219], v[152:153], v[218:219]
	v_pk_mul_f32 v[220:221], v[220:221], v[120:121]
	v_cvt_pk_bf16_f32 v214, v218, v219
	v_cvt_pk_bf16_f32 v196, v220, v221
	v_rcp_f32_e32 v220, v154
	v_rcp_f32_e32 v221, v155
	v_lshlrev_b32_e32 v218, 16, v13
	v_and_b32_e32 v219, 0xffff0000, v13
	v_pk_mul_f32 v[218:219], v[154:155], v[218:219]
	v_pk_mul_f32 v[220:221], v[220:221], v[122:123]
	v_cvt_pk_bf16_f32 v215, v218, v219
	v_cvt_pk_bf16_f32 v197, v220, v221
	v_rcp_f32_e32 v220, v156
	v_rcp_f32_e32 v221, v157
	v_lshlrev_b32_e32 v218, 16, v14
	v_and_b32_e32 v219, 0xffff0000, v14
	v_pk_mul_f32 v[218:219], v[156:157], v[218:219]
	v_pk_mul_f32 v[220:221], v[220:221], v[124:125]
	v_cvt_pk_bf16_f32 v216, v218, v219
	v_cvt_pk_bf16_f32 v198, v220, v221
	v_rcp_f32_e32 v220, v158
	v_rcp_f32_e32 v221, v159
	v_lshlrev_b32_e32 v218, 16, v15
	v_and_b32_e32 v219, 0xffff0000, v15
	v_pk_mul_f32 v[218:219], v[158:159], v[218:219]
	v_pk_mul_f32 v[220:221], v[220:221], v[126:127]
	v_cvt_pk_bf16_f32 v217, v218, v219
	v_cvt_pk_bf16_f32 v199, v220, v221
	ds_write_b128 v222, v[184:187] offset:1024
	ds_write_b128 v223, v[188:191] offset:1024
	ds_write_b128 v224, v[192:195] offset:1024
	ds_write_b128 v225, v[196:199] offset:1024
	ds_write_b128 v226, v[202:205]
	ds_write_b128 v226, v[206:209] offset:16
	ds_write_b128 v226, v[210:213] offset:32
	ds_write_b128 v226, v[214:217] offset:48
	s_waitcnt lgkmcnt(0)
	s_barrier
	s_waitcnt vmcnt(2)
	ds_read_b128 v[234:237], v248
	ds_read_b128 v[238:241], v249
	ds_read_b128 v[242:245], v250
	ds_read_b128 v[168:171], v251
	ds_read_b128 v[0:3], v248 offset:4096
	ds_read_b128 v[4:7], v249 offset:4096
	ds_read_b128 v[8:11], v250 offset:4096
	ds_read_b128 v[12:15], v251 offset:4096
	s_cmp_eq_u32 s70, 31
	s_cselect_b32 s76, 0, s33
	s_add_u32 s1, s72, s77
	s_add_u32 s77, s77, 0x4000
	s_cmp_eq_u32 s77, 0x10400
	s_cselect_b32 s77, 0x24000, s77
	s_cmp_eq_u32 s77, 0x28000
	s_cselect_b32 s77, 0x8400, s77
	s_waitcnt lgkmcnt(4)
	s_add_u32 m0, s1, 0
	s_nop 0
	global_load_lds_dwordx4 v252, s[34:35]
	v_lshlrev_b32_e32 v96, 16, v234
	v_and_b32_e32 v97, 0xffff0000, v234
	v_lshlrev_b32_e32 v98, 16, v235
	v_and_b32_e32 v99, 0xffff0000, v235
	v_lshlrev_b32_e32 v100, 16, v236
	v_and_b32_e32 v101, 0xffff0000, v236
	v_lshlrev_b32_e32 v102, 16, v237
	v_and_b32_e32 v103, 0xffff0000, v237
	v_lshlrev_b32_e32 v104, 16, v238
	v_and_b32_e32 v105, 0xffff0000, v238
	v_lshlrev_b32_e32 v106, 16, v239
	v_and_b32_e32 v107, 0xffff0000, v239
	v_lshlrev_b32_e32 v108, 16, v240
	v_and_b32_e32 v109, 0xffff0000, v240
	v_lshlrev_b32_e32 v110, 16, v241
	v_and_b32_e32 v111, 0xffff0000, v241
	v_lshlrev_b32_e32 v112, 16, v242
	v_and_b32_e32 v113, 0xffff0000, v242
	v_lshlrev_b32_e32 v114, 16, v243
	v_and_b32_e32 v115, 0xffff0000, v243
	v_lshlrev_b32_e32 v116, 16, v244
	s_add_u32 m0, s1, 1024
	s_nop 0
	global_load_lds_dwordx4 v253, s[34:35]
	v_and_b32_e32 v117, 0xffff0000, v244
	v_lshlrev_b32_e32 v118, 16, v245
	v_and_b32_e32 v119, 0xffff0000, v245
	v_lshlrev_b32_e32 v120, 16, v168
	v_and_b32_e32 v121, 0xffff0000, v168
	v_lshlrev_b32_e32 v122, 16, v169
	v_and_b32_e32 v123, 0xffff0000, v169
	v_lshlrev_b32_e32 v124, 16, v170
	v_and_b32_e32 v125, 0xffff0000, v170
	v_lshlrev_b32_e32 v126, 16, v171
	v_and_b32_e32 v127, 0xffff0000, v171
	s_waitcnt lgkmcnt(0)
	v_sub_f32_e32 v128, 1.0, v96
	v_sub_f32_e32 v129, 1.0, v97
	v_sub_f32_e32 v130, 1.0, v98
	v_sub_f32_e32 v131, 1.0, v99
	v_sub_f32_e32 v132, 1.0, v100
	v_sub_f32_e32 v133, 1.0, v101
	v_sub_f32_e32 v134, 1.0, v102
	v_sub_f32_e32 v135, 1.0, v103
	v_sub_f32_e32 v136, 1.0, v104
	v_sub_f32_e32 v137, 1.0, v105
	s_add_u32 m0, s1, 2048
	s_nop 0
	global_load_lds_dwordx4 v254, s[34:35]
	v_sub_f32_e32 v138, 1.0, v106
	v_sub_f32_e32 v139, 1.0, v107
	v_sub_f32_e32 v140, 1.0, v108
	v_sub_f32_e32 v141, 1.0, v109
	v_sub_f32_e32 v142, 1.0, v110
	v_sub_f32_e32 v143, 1.0, v111
	v_sub_f32_e32 v144, 1.0, v112
	v_sub_f32_e32 v145, 1.0, v113
	v_sub_f32_e32 v146, 1.0, v114
	v_sub_f32_e32 v147, 1.0, v115
	v_sub_f32_e32 v148, 1.0, v116
	v_sub_f32_e32 v149, 1.0, v117
	v_sub_f32_e32 v150, 1.0, v118
	v_sub_f32_e32 v151, 1.0, v119
	v_sub_f32_e32 v152, 1.0, v120
	v_sub_f32_e32 v153, 1.0, v121
	v_sub_f32_e32 v154, 1.0, v122
	v_sub_f32_e32 v155, 1.0, v123
	v_sub_f32_e32 v156, 1.0, v124
	v_sub_f32_e32 v157, 1.0, v125
	v_sub_f32_e32 v158, 1.0, v126
	s_add_u32 m0, s1, 3072
	s_nop 0
	global_load_lds_dwordx4 v255, s[34:35]
	v_add_u32_e32 v252, s76, v252
	v_add_u32_e32 v253, s76, v253
	v_add_u32_e32 v254, s76, v254
	v_add_u32_e32 v255, s76, v255
	v_sub_f32_e32 v159, 1.0, v127
	v_mul_f32_dpp v128, v128, v128 row_shr:1 row_mask:0xf bank_mask:0xf
	v_mul_f32_dpp v129, v129, v129 row_shr:1 row_mask:0xf bank_mask:0xf
	v_mul_f32_dpp v130, v130, v130 row_shr:1 row_mask:0xf bank_mask:0xf
	v_mul_f32_dpp v131, v131, v131 row_shr:1 row_mask:0xf bank_mask:0xf
	v_mul_f32_dpp v132, v132, v132 row_shr:1 row_mask:0xf bank_mask:0xf
	v_mul_f32_dpp v133, v133, v133 row_shr:1 row_mask:0xf bank_mask:0xf
	v_mul_f32_dpp v134, v134, v134 row_shr:1 row_mask:0xf bank_mask:0xf
	v_mul_f32_dpp v135, v135, v135 row_shr:1 row_mask:0xf bank_mask:0xf
	v_mul_f32_dpp v136, v136, v136 row_shr:1 row_mask:0xf bank_mask:0xf
	v_mul_f32_dpp v137, v137, v137 row_shr:1 row_mask:0xf bank_mask:0xf
	v_mul_f32_dpp v138, v138, v138 row_shr:1 row_mask:0xf bank_mask:0xf
	v_mul_f32_dpp v139, v139, v139 row_shr:1 row_mask:0xf bank_mask:0xf
	v_mul_f32_dpp v140, v140, v140 row_shr:1 row_mask:0xf bank_mask:0xf
	v_mul_f32_dpp v141, v141, v141 row_shr:1 row_mask:0xf bank_mask:0xf
	v_mul_f32_dpp v142, v142, v142 row_shr:1 row_mask:0xf bank_mask:0xf
	v_mul_f32_dpp v143, v143, v143 row_shr:1 row_mask:0xf bank_mask:0xf
	v_mul_f32_dpp v144, v144, v144 row_shr:1 row_mask:0xf bank_mask:0xf
	v_mul_f32_dpp v145, v145, v145 row_shr:1 row_mask:0xf bank_mask:0xf
	v_mul_f32_dpp v146, v146, v146 row_shr:1 row_mask:0xf bank_mask:0xf
	v_mul_f32_dpp v147, v147, v147 row_shr:1 row_mask:0xf bank_mask:0xf
	s_add_u32 m0, s71, 0
	s_nop 0
	global_load_lds_dwordx4 v228, s[14:15]
	v_mul_f32_dpp v148, v148, v148 row_shr:1 row_mask:0xf bank_mask:0xf
	v_mul_f32_dpp v149, v149, v149 row_shr:1 row_mask:0xf bank_mask:0xf
	v_mul_f32_dpp v150, v150, v150 row_shr:1 row_mask:0xf bank_mask:0xf
	v_mul_f32_dpp v151, v151, v151 row_shr:1 row_mask:0xf bank_mask:0xf
	v_mul_f32_dpp v152, v152, v152 row_shr:1 row_mask:0xf bank_mask:0xf
	v_mul_f32_dpp v153, v153, v153 row_shr:1 row_mask:0xf bank_mask:0xf
	v_mul_f32_dpp v154, v154, v154 row_shr:1 row_mask:0xf bank_mask:0xf
	v_mul_f32_dpp v155, v155, v155 row_shr:1 row_mask:0xf bank_mask:0xf
	v_mul_f32_dpp v156, v156, v156 row_shr:1 row_mask:0xf bank_mask:0xf
	v_mul_f32_dpp v157, v157, v157 row_shr:1 row_mask:0xf bank_mask:0xf
	v_mul_f32_dpp v158, v158, v158 row_shr:1 row_mask:0xf bank_mask:0xf
	v_mul_f32_dpp v159, v159, v159 row_shr:1 row_mask:0xf bank_mask:0xf
	v_mul_f32_dpp v128, v128, v128 row_shr:2 row_mask:0xf bank_mask:0xf
	v_mul_f32_dpp v129, v129, v129 row_shr:2 row_mask:0xf bank_mask:0xf
	v_mul_f32_dpp v130, v130, v130 row_shr:2 row_mask:0xf bank_mask:0xf
	v_mul_f32_dpp v131, v131, v131 row_shr:2 row_mask:0xf bank_mask:0xf
	v_mul_f32_dpp v132, v132, v132 row_shr:2 row_mask:0xf bank_mask:0xf
	v_mul_f32_dpp v133, v133, v133 row_shr:2 row_mask:0xf bank_mask:0xf
	v_mul_f32_dpp v134, v134, v134 row_shr:2 row_mask:0xf bank_mask:0xf
	v_mul_f32_dpp v135, v135, v135 row_shr:2 row_mask:0xf bank_mask:0xf
	v_mul_f32_dpp v136, v136, v136 row_shr:2 row_mask:0xf bank_mask:0xf
	s_add_u32 m0, s71, 4096
	s_nop 0
	global_load_lds_dwordx4 v228, s[30:31]
	v_mul_f32_dpp v137, v137, v137 row_shr:2 row_mask:0xf bank_mask:0xf
	v_mul_f32_dpp v138, v138, v138 row_shr:2 row_mask:0xf bank_mask:0xf
	v_mul_f32_dpp v139, v139, v139 row_shr:2 row_mask:0xf bank_mask:0xf
	v_mul_f32_dpp v140, v140, v140 row_shr:2 row_mask:0xf bank_mask:0xf
	v_mul_f32_dpp v141, v141, v141 row_shr:2 row_mask:0xf bank_mask:0xf
	v_mul_f32_dpp v142, v142, v142 row_shr:2 row_mask:0xf bank_mask:0xf
	v_mul_f32_dpp v143, v143, v143 row_shr:2 row_mask:0xf bank_mask:0xf
	v_mul_f32_dpp v144, v144, v144 row_shr:2 row_mask:0xf bank_mask:0xf
	v_mul_f32_dpp v145, v145, v145 row_shr:2 row_mask:0xf bank_mask:0xf
	v_mul_f32_dpp v146, v146, v146 row_shr:2 row_mask:0xf bank_mask:0xf
	v_mul_f32_dpp v147, v147, v147 row_shr:2 row_mask:0xf bank_mask:0xf
	v_mul_f32_dpp v148, v148, v148 row_shr:2 row_mask:0xf bank_mask:0xf
	v_mul_f32_dpp v149, v149, v149 row_shr:2 row_mask:0xf bank_mask:0xf
	v_mul_f32_dpp v150, v150, v150 row_shr:2 row_mask:0xf bank_mask:0xf
	v_mul_f32_dpp v151, v151, v151 row_shr:2 row_mask:0xf bank_mask:0xf
	v_mul_f32_dpp v152, v152, v152 row_shr:2 row_mask:0xf bank_mask:0xf
	v_mul_f32_dpp v153, v153, v153 row_shr:2 row_mask:0xf bank_mask:0xf
	v_mul_f32_dpp v154, v154, v154 row_shr:2 row_mask:0xf bank_mask:0xf
	v_mul_f32_dpp v155, v155, v155 row_shr:2 row_mask:0xf bank_mask:0xf
	v_mul_f32_dpp v156, v156, v156 row_shr:2 row_mask:0xf bank_mask:0xf
	v_mul_f32_dpp v157, v157, v157 row_shr:2 row_mask:0xf bank_mask:0xf
	s_add_u32 m0, s71, 1024
	s_nop 0
	global_load_lds_dwordx4 v230, s[14:15]
	v_mul_f32_dpp v158, v158, v158 row_shr:2 row_mask:0xf bank_mask:0xf
	v_mul_f32_dpp v159, v159, v159 row_shr:2 row_mask:0xf bank_mask:0xf
	v_mul_f32_dpp v128, v128, v128 row_shr:4 row_mask:0xf bank_mask:0xf
	v_mul_f32_dpp v129, v129, v129 row_shr:4 row_mask:0xf bank_mask:0xf
	v_mul_f32_dpp v130, v130, v130 row_shr:4 row_mask:0xf bank_mask:0xf
	v_mul_f32_dpp v131, v131, v131 row_shr:4 row_mask:0xf bank_mask:0xf
	v_mul_f32_dpp v132, v132, v132 row_shr:4 row_mask:0xf bank_mask:0xf
	v_mul_f32_dpp v133, v133, v133 row_shr:4 row_mask:0xf bank_mask:0xf
	v_mul_f32_dpp v134, v134, v134 row_shr:4 row_mask:0xf bank_mask:0xf
	v_mul_f32_dpp v135, v135, v135 row_shr:4 row_mask:0xf bank_mask:0xf
	v_mul_f32_dpp v136, v136, v136 row_shr:4 row_mask:0xf bank_mask:0xf
	v_mul_f32_dpp v137, v137, v137 row_shr:4 row_mask:0xf bank_mask:0xf
	v_mul_f32_dpp v138, v138, v138 row_shr:4 row_mask:0xf bank_mask:0xf
	v_mul_f32_dpp v139, v139, v139 row_shr:4 row_mask:0xf bank_mask:0xf
	v_mul_f32_dpp v140, v140, v140 row_shr:4 row_mask:0xf bank_mask:0xf
	v_mul_f32_dpp v141, v141, v141 row_shr:4 row_mask:0xf bank_mask:0xf
	v_mul_f32_dpp v142, v142, v142 row_shr:4 row_mask:0xf bank_mask:0xf
	v_mul_f32_dpp v143, v143, v143 row_shr:4 row_mask:0xf bank_mask:0xf
	v_mul_f32_dpp v144, v144, v144 row_shr:4 row_mask:0xf bank_mask:0xf
	v_mul_f32_dpp v145, v145, v145 row_shr:4 row_mask:0xf bank_mask:0xf
	v_mul_f32_dpp v146, v146, v146 row_shr:4 row_mask:0xf bank_mask:0xf
	s_add_u32 m0, s71, 5120
	s_nop 0
	global_load_lds_dwordx4 v230, s[30:31]
	v_mul_f32_dpp v147, v147, v147 row_shr:4 row_mask:0xf bank_mask:0xf
	v_mul_f32_dpp v148, v148, v148 row_shr:4 row_mask:0xf bank_mask:0xf
	v_mul_f32_dpp v149, v149, v149 row_shr:4 row_mask:0xf bank_mask:0xf
	v_mul_f32_dpp v150, v150, v150 row_shr:4 row_mask:0xf bank_mask:0xf
	v_mul_f32_dpp v151, v151, v151 row_shr:4 row_mask:0xf bank_mask:0xf
	v_mul_f32_dpp v152, v152, v152 row_shr:4 row_mask:0xf bank_mask:0xf
	v_mul_f32_dpp v153, v153, v153 row_shr:4 row_mask:0xf bank_mask:0xf
	v_mul_f32_dpp v154, v154, v154 row_shr:4 row_mask:0xf bank_mask:0xf
	v_mul_f32_dpp v155, v155, v155 row_shr:4 row_mask:0xf bank_mask:0xf
	v_mul_f32_dpp v156, v156, v156 row_shr:4 row_mask:0xf bank_mask:0xf
	v_mul_f32_dpp v157, v157, v157 row_shr:4 row_mask:0xf bank_mask:0xf
	v_mul_f32_dpp v158, v158, v158 row_shr:4 row_mask:0xf bank_mask:0xf
	v_mul_f32_dpp v159, v159, v159 row_shr:4 row_mask:0xf bank_mask:0xf
	v_mul_f32_dpp v128, v128, v128 row_shr:8 row_mask:0xf bank_mask:0xf
	v_mul_f32_dpp v129, v129, v129 row_shr:8 row_mask:0xf bank_mask:0xf
	v_mul_f32_dpp v130, v130, v130 row_shr:8 row_mask:0xf bank_mask:0xf
	v_mul_f32_dpp v131, v131, v131 row_shr:8 row_mask:0xf bank_mask:0xf
	v_mul_f32_dpp v132, v132, v132 row_shr:8 row_mask:0xf bank_mask:0xf
	v_mul_f32_dpp v133, v133, v133 row_shr:8 row_mask:0xf bank_mask:0xf
	v_mul_f32_dpp v134, v134, v134 row_shr:8 row_mask:0xf bank_mask:0xf
	v_mul_f32_dpp v135, v135, v135 row_shr:8 row_mask:0xf bank_mask:0xf
	s_add_u32 m0, s71, 2048
	s_nop 0
	global_load_lds_dwordx4 v231, s[14:15]
	v_mul_f32_dpp v136, v136, v136 row_shr:8 row_mask:0xf bank_mask:0xf
	v_mul_f32_dpp v137, v137, v137 row_shr:8 row_mask:0xf bank_mask:0xf
	v_mul_f32_dpp v138, v138, v138 row_shr:8 row_mask:0xf bank_mask:0xf
	v_mul_f32_dpp v139, v139, v139 row_shr:8 row_mask:0xf bank_mask:0xf
	v_mul_f32_dpp v140, v140, v140 row_shr:8 row_mask:0xf bank_mask:0xf
	v_mul_f32_dpp v141, v141, v141 row_shr:8 row_mask:0xf bank_mask:0xf
	v_mul_f32_dpp v142, v142, v142 row_shr:8 row_mask:0xf bank_mask:0xf
	v_mul_f32_dpp v143, v143, v143 row_shr:8 row_mask:0xf bank_mask:0xf
	v_mul_f32_dpp v144, v144, v144 row_shr:8 row_mask:0xf bank_mask:0xf
	v_mul_f32_dpp v145, v145, v145 row_shr:8 row_mask:0xf bank_mask:0xf
	v_mul_f32_dpp v146, v146, v146 row_shr:8 row_mask:0xf bank_mask:0xf
	v_mul_f32_dpp v147, v147, v147 row_shr:8 row_mask:0xf bank_mask:0xf
	v_mul_f32_dpp v148, v148, v148 row_shr:8 row_mask:0xf bank_mask:0xf
	v_mul_f32_dpp v149, v149, v149 row_shr:8 row_mask:0xf bank_mask:0xf
	v_mul_f32_dpp v150, v150, v150 row_shr:8 row_mask:0xf bank_mask:0xf
	v_mul_f32_dpp v151, v151, v151 row_shr:8 row_mask:0xf bank_mask:0xf
	v_mul_f32_dpp v152, v152, v152 row_shr:8 row_mask:0xf bank_mask:0xf
	v_mul_f32_dpp v153, v153, v153 row_shr:8 row_mask:0xf bank_mask:0xf
	v_mul_f32_dpp v154, v154, v154 row_shr:8 row_mask:0xf bank_mask:0xf
	v_mul_f32_dpp v155, v155, v155 row_shr:8 row_mask:0xf bank_mask:0xf
	v_mul_f32_dpp v156, v156, v156 row_shr:8 row_mask:0xf bank_mask:0xf
	s_add_u32 m0, s71, 6144
	s_nop 0
	global_load_lds_dwordx4 v231, s[30:31]
	v_mul_f32_dpp v157, v157, v157 row_shr:8 row_mask:0xf bank_mask:0xf
	v_mul_f32_dpp v158, v158, v158 row_shr:8 row_mask:0xf bank_mask:0xf
	v_mul_f32_dpp v159, v159, v159 row_shr:8 row_mask:0xf bank_mask:0xf
	v_mul_f32_dpp v128, v128, v128 row_bcast:15 row_mask:0xa bank_mask:0xf
	v_mul_f32_dpp v129, v129, v129 row_bcast:15 row_mask:0xa bank_mask:0xf
	v_mul_f32_dpp v130, v130, v130 row_bcast:15 row_mask:0xa bank_mask:0xf
	v_mul_f32_dpp v131, v131, v131 row_bcast:15 row_mask:0xa bank_mask:0xf
	v_mul_f32_dpp v132, v132, v132 row_bcast:15 row_mask:0xa bank_mask:0xf
	v_mul_f32_dpp v133, v133, v133 row_bcast:15 row_mask:0xa bank_mask:0xf
	v_mul_f32_dpp v134, v134, v134 row_bcast:15 row_mask:0xa bank_mask:0xf
	v_mul_f32_dpp v135, v135, v135 row_bcast:15 row_mask:0xa bank_mask:0xf
	v_mul_f32_dpp v136, v136, v136 row_bcast:15 row_mask:0xa bank_mask:0xf
	v_mul_f32_dpp v137, v137, v137 row_bcast:15 row_mask:0xa bank_mask:0xf
	v_mul_f32_dpp v138, v138, v138 row_bcast:15 row_mask:0xa bank_mask:0xf
	v_mul_f32_dpp v139, v139, v139 row_bcast:15 row_mask:0xa bank_mask:0xf
	v_mul_f32_dpp v140, v140, v140 row_bcast:15 row_mask:0xa bank_mask:0xf
	v_mul_f32_dpp v141, v141, v141 row_bcast:15 row_mask:0xa bank_mask:0xf
	v_mul_f32_dpp v142, v142, v142 row_bcast:15 row_mask:0xa bank_mask:0xf
	v_mul_f32_dpp v143, v143, v143 row_bcast:15 row_mask:0xa bank_mask:0xf
	v_mul_f32_dpp v144, v144, v144 row_bcast:15 row_mask:0xa bank_mask:0xf
	v_mul_f32_dpp v145, v145, v145 row_bcast:15 row_mask:0xa bank_mask:0xf
	s_add_u32 m0, s71, 3072
	s_nop 0
	global_load_lds_dwordx4 v232, s[14:15]
	v_mul_f32_dpp v146, v146, v146 row_bcast:15 row_mask:0xa bank_mask:0xf
	v_mul_f32_dpp v147, v147, v147 row_bcast:15 row_mask:0xa bank_mask:0xf
	v_mul_f32_dpp v148, v148, v148 row_bcast:15 row_mask:0xa bank_mask:0xf
	v_mul_f32_dpp v149, v149, v149 row_bcast:15 row_mask:0xa bank_mask:0xf
	v_mul_f32_dpp v150, v150, v150 row_bcast:15 row_mask:0xa bank_mask:0xf
	v_mul_f32_dpp v151, v151, v151 row_bcast:15 row_mask:0xa bank_mask:0xf
	v_mul_f32_dpp v152, v152, v152 row_bcast:15 row_mask:0xa bank_mask:0xf
	v_mul_f32_dpp v153, v153, v153 row_bcast:15 row_mask:0xa bank_mask:0xf
	v_mul_f32_dpp v154, v154, v154 row_bcast:15 row_mask:0xa bank_mask:0xf
	v_mul_f32_dpp v155, v155, v155 row_bcast:15 row_mask:0xa bank_mask:0xf
	v_mul_f32_dpp v156, v156, v156 row_bcast:15 row_mask:0xa bank_mask:0xf
	v_mul_f32_dpp v157, v157, v157 row_bcast:15 row_mask:0xa bank_mask:0xf
	v_mul_f32_dpp v158, v158, v158 row_bcast:15 row_mask:0xa bank_mask:0xf
	v_mul_f32_dpp v159, v159, v159 row_bcast:15 row_mask:0xa bank_mask:0xf
	v_mul_f32_dpp v128, v128, v128 row_bcast:31 row_mask:0xc bank_mask:0xf
	v_mul_f32_dpp v129, v129, v129 row_bcast:31 row_mask:0xc bank_mask:0xf
	v_mul_f32_dpp v130, v130, v130 row_bcast:31 row_mask:0xc bank_mask:0xf
	v_mul_f32_dpp v131, v131, v131 row_bcast:31 row_mask:0xc bank_mask:0xf
	v_mul_f32_dpp v132, v132, v132 row_bcast:31 row_mask:0xc bank_mask:0xf
	v_mul_f32_dpp v133, v133, v133 row_bcast:31 row_mask:0xc bank_mask:0xf
	v_mul_f32_dpp v134, v134, v134 row_bcast:31 row_mask:0xc bank_mask:0xf
	s_add_u32 m0, s71, 7168
	s_nop 0
	global_load_lds_dwordx4 v232, s[30:31]
	v_add_u32_e32 v228, s76, v228
	v_add_u32_e32 v230, s76, v230
	v_add_u32_e32 v231, s76, v231
	v_add_u32_e32 v232, s76, v232
	v_mul_f32_dpp v135, v135, v135 row_bcast:31 row_mask:0xc bank_mask:0xf
	v_mul_f32_dpp v136, v136, v136 row_bcast:31 row_mask:0xc bank_mask:0xf
	v_mul_f32_dpp v137, v137, v137 row_bcast:31 row_mask:0xc bank_mask:0xf
	v_mul_f32_dpp v138, v138, v138 row_bcast:31 row_mask:0xc bank_mask:0xf
	v_mul_f32_dpp v139, v139, v139 row_bcast:31 row_mask:0xc bank_mask:0xf
	v_mul_f32_dpp v140, v140, v140 row_bcast:31 row_mask:0xc bank_mask:0xf
	v_mul_f32_dpp v141, v141, v141 row_bcast:31 row_mask:0xc bank_mask:0xf
	v_mul_f32_dpp v142, v142, v142 row_bcast:31 row_mask:0xc bank_mask:0xf
	v_mul_f32_dpp v143, v143, v143 row_bcast:31 row_mask:0xc bank_mask:0xf
	v_mul_f32_dpp v144, v144, v144 row_bcast:31 row_mask:0xc bank_mask:0xf
	v_mul_f32_dpp v145, v145, v145 row_bcast:31 row_mask:0xc bank_mask:0xf
	v_mul_f32_dpp v146, v146, v146 row_bcast:31 row_mask:0xc bank_mask:0xf
	v_mul_f32_dpp v147, v147, v147 row_bcast:31 row_mask:0xc bank_mask:0xf
	v_mul_f32_dpp v148, v148, v148 row_bcast:31 row_mask:0xc bank_mask:0xf
	v_mul_f32_dpp v149, v149, v149 row_bcast:31 row_mask:0xc bank_mask:0xf
	v_mul_f32_dpp v150, v150, v150 row_bcast:31 row_mask:0xc bank_mask:0xf
	v_mul_f32_dpp v151, v151, v151 row_bcast:31 row_mask:0xc bank_mask:0xf
	v_mul_f32_dpp v152, v152, v152 row_bcast:31 row_mask:0xc bank_mask:0xf
	v_mul_f32_dpp v153, v153, v153 row_bcast:31 row_mask:0xc bank_mask:0xf
	v_mul_f32_dpp v154, v154, v154 row_bcast:31 row_mask:0xc bank_mask:0xf
	v_mul_f32_dpp v155, v155, v155 row_bcast:31 row_mask:0xc bank_mask:0xf
	v_mul_f32_dpp v156, v156, v156 row_bcast:31 row_mask:0xc bank_mask:0xf
	v_mul_f32_dpp v157, v157, v157 row_bcast:31 row_mask:0xc bank_mask:0xf
	v_mul_f32_dpp v158, v158, v158 row_bcast:31 row_mask:0xc bank_mask:0xf
	v_mul_f32_dpp v159, v159, v159 row_bcast:31 row_mask:0xc bank_mask:0xf
	s_cmp_ge_u32 s70, 30
	s_cselect_b32 s75, 0, s33
	global_load_dword v16, v18, s[82:83]
	global_load_dword v17, v18, s[82:83] offset:128
	v_add_u32_e32 v18, s75, v18
	s_mov_b32 exec_lo, 0
	s_brev_b32 exec_hi, 1
	ds_write_b128 v247, v[128:131] offset:512
	ds_write_b128 v247, v[132:135] offset:528
	ds_write_b128 v247, v[136:139] offset:544
	ds_write_b128 v247, v[140:143] offset:560
	ds_write_b128 v247, v[144:147] offset:576
	ds_write_b128 v247, v[148:151] offset:592
	ds_write_b128 v247, v[152:155] offset:608
	ds_write_b128 v247, v[156:159] offset:624
	s_mov_b64 exec, -1
	v_rcp_f32_e32 v220, v128
	v_rcp_f32_e32 v221, v129
	v_lshlrev_b32_e32 v218, 16, v0
	v_and_b32_e32 v219, 0xffff0000, v0
	v_pk_mul_f32 v[218:219], v[128:129], v[218:219]
	v_pk_mul_f32 v[220:221], v[220:221], v[96:97]
	v_cvt_pk_bf16_f32 v202, v218, v219
	v_cvt_pk_bf16_f32 v184, v220, v221
	v_rcp_f32_e32 v220, v130
	v_rcp_f32_e32 v221, v131
	v_lshlrev_b32_e32 v218, 16, v1
	v_and_b32_e32 v219, 0xffff0000, v1
	v_pk_mul_f32 v[218:219], v[130:131], v[218:219]
	v_pk_mul_f32 v[220:221], v[220:221], v[98:99]
	v_cvt_pk_bf16_f32 v203, v218, v219
	v_cvt_pk_bf16_f32 v185, v220, v221
	v_rcp_f32_e32 v220, v132
	v_rcp_f32_e32 v221, v133
	v_lshlrev_b32_e32 v218, 16, v2
	v_and_b32_e32 v219, 0xffff0000, v2
	v_pk_mul_f32 v[218:219], v[132:133], v[218:219]
	v_pk_mul_f32 v[220:221], v[220:221], v[100:101]
	v_cvt_pk_bf16_f32 v204, v218, v219
	v_cvt_pk_bf16_f32 v186, v220, v221
	v_rcp_f32_e32 v220, v134
	v_rcp_f32_e32 v221, v135
	v_lshlrev_b32_e32 v218, 16, v3
	v_and_b32_e32 v219, 0xffff0000, v3
	v_pk_mul_f32 v[218:219], v[134:135], v[218:219]
	v_pk_mul_f32 v[220:221], v[220:221], v[102:103]
	v_cvt_pk_bf16_f32 v205, v218, v219
	v_cvt_pk_bf16_f32 v187, v220, v221
	v_rcp_f32_e32 v220, v136
	v_rcp_f32_e32 v221, v137
	v_lshlrev_b32_e32 v218, 16, v4
	v_and_b32_e32 v219, 0xffff0000, v4
	v_pk_mul_f32 v[218:219], v[136:137], v[218:219]
	v_pk_mul_f32 v[220:221], v[220:221], v[104:105]
	v_cvt_pk_bf16_f32 v206, v218, v219
	v_cvt_pk_bf16_f32 v188, v220, v221
	v_rcp_f32_e32 v220, v138
	v_rcp_f32_e32 v221, v139
	v_lshlrev_b32_e32 v218, 16, v5
	v_and_b32_e32 v219, 0xffff0000, v5
	v_pk_mul_f32 v[218:219], v[138:139], v[218:219]
	v_pk_mul_f32 v[220:221], v[220:221], v[106:107]
	v_cvt_pk_bf16_f32 v207, v218, v219
	v_cvt_pk_bf16_f32 v189, v220, v221
	v_rcp_f32_e32 v220, v140
	v_rcp_f32_e32 v221, v141
	v_lshlrev_b32_e32 v218, 16, v6
	v_and_b32_e32 v219, 0xffff0000, v6
	v_pk_mul_f32 v[218:219], v[140:141], v[218:219]
	v_pk_mul_f32 v[220:221], v[220:221], v[108:109]
	v_cvt_pk_bf16_f32 v208, v218, v219
	v_cvt_pk_bf16_f32 v190, v220, v221
	v_rcp_f32_e32 v220, v142
	v_rcp_f32_e32 v221, v143
	v_lshlrev_b32_e32 v218, 16, v7
	v_and_b32_e32 v219, 0xffff0000, v7
	v_pk_mul_f32 v[218:219], v[142:143], v[218:219]
	v_pk_mul_f32 v[220:221], v[220:221], v[110:111]
	v_cvt_pk_bf16_f32 v209, v218, v219
	v_cvt_pk_bf16_f32 v191, v220, v221
	v_rcp_f32_e32 v220, v144
	v_rcp_f32_e32 v221, v145
	v_lshlrev_b32_e32 v218, 16, v8
	v_and_b32_e32 v219, 0xffff0000, v8
	v_pk_mul_f32 v[218:219], v[144:145], v[218:219]
	v_pk_mul_f32 v[220:221], v[220:221], v[112:113]
	v_cvt_pk_bf16_f32 v210, v218, v219
	v_cvt_pk_bf16_f32 v192, v220, v221
	v_rcp_f32_e32 v220, v146
	v_rcp_f32_e32 v221, v147
	v_lshlrev_b32_e32 v218, 16, v9
	v_and_b32_e32 v219, 0xffff0000, v9
	v_pk_mul_f32 v[218:219], v[146:147], v[218:219]
	v_pk_mul_f32 v[220:221], v[220:221], v[114:115]
	v_cvt_pk_bf16_f32 v211, v218, v219
	v_cvt_pk_bf16_f32 v193, v220, v221
	v_rcp_f32_e32 v220, v148
	v_rcp_f32_e32 v221, v149
	v_lshlrev_b32_e32 v218, 16, v10
	v_and_b32_e32 v219, 0xffff0000, v10
	v_pk_mul_f32 v[218:219], v[148:149], v[218:219]
	v_pk_mul_f32 v[220:221], v[220:221], v[116:117]
	v_cvt_pk_bf16_f32 v212, v218, v219
	v_cvt_pk_bf16_f32 v194, v220, v221
	v_rcp_f32_e32 v220, v150
	v_rcp_f32_e32 v221, v151
	v_lshlrev_b32_e32 v218, 16, v11
	v_and_b32_e32 v219, 0xffff0000, v11
	v_pk_mul_f32 v[218:219], v[150:151], v[218:219]
	v_pk_mul_f32 v[220:221], v[220:221], v[118:119]
	v_cvt_pk_bf16_f32 v213, v218, v219
	v_cvt_pk_bf16_f32 v195, v220, v221
	v_rcp_f32_e32 v220, v152
	v_rcp_f32_e32 v221, v153
	v_lshlrev_b32_e32 v218, 16, v12
	v_and_b32_e32 v219, 0xffff0000, v12
	v_pk_mul_f32 v[218:219], v[152:153], v[218:219]
	v_pk_mul_f32 v[220:221], v[220:221], v[120:121]
	v_cvt_pk_bf16_f32 v214, v218, v219
	v_cvt_pk_bf16_f32 v196, v220, v221
	v_rcp_f32_e32 v220, v154
	v_rcp_f32_e32 v221, v155
	v_lshlrev_b32_e32 v218, 16, v13
	v_and_b32_e32 v219, 0xffff0000, v13
	v_pk_mul_f32 v[218:219], v[154:155], v[218:219]
	v_pk_mul_f32 v[220:221], v[220:221], v[122:123]
	v_cvt_pk_bf16_f32 v215, v218, v219
	v_cvt_pk_bf16_f32 v197, v220, v221
	v_rcp_f32_e32 v220, v156
	v_rcp_f32_e32 v221, v157
	v_lshlrev_b32_e32 v218, 16, v14
	v_and_b32_e32 v219, 0xffff0000, v14
	v_pk_mul_f32 v[218:219], v[156:157], v[218:219]
	v_pk_mul_f32 v[220:221], v[220:221], v[124:125]
	v_cvt_pk_bf16_f32 v216, v218, v219
	v_cvt_pk_bf16_f32 v198, v220, v221
	v_rcp_f32_e32 v220, v158
	v_rcp_f32_e32 v221, v159
	v_lshlrev_b32_e32 v218, 16, v15
	v_and_b32_e32 v219, 0xffff0000, v15
	v_pk_mul_f32 v[218:219], v[158:159], v[218:219]
	v_pk_mul_f32 v[220:221], v[220:221], v[126:127]
	v_cvt_pk_bf16_f32 v217, v218, v219
	v_cvt_pk_bf16_f32 v199, v220, v221
	ds_write_b128 v222, v[184:187] offset:17408
	ds_write_b128 v223, v[188:191] offset:17408
	ds_write_b128 v224, v[192:195] offset:17408
	ds_write_b128 v225, v[196:199] offset:17408
	ds_write_b128 v227, v[202:205]
	ds_write_b128 v227, v[206:209] offset:16
	ds_write_b128 v227, v[210:213] offset:32
	ds_write_b128 v227, v[214:217] offset:48
	s_waitcnt lgkmcnt(0)
	s_barrier
	s_add_u32 s70, s70, 1
	s_cmp_lt_u32 s70, 32
	s_cbranch_scc1 .Lh2_prep_loop
	s_waitcnt vmcnt(0)
	s_barrier
	s_branch .Lh2_done
